# static s_setprio 1 at kernel entry for workgroups in the upper half of the grid (the co-resident later block)
# baseline (speedup 1.0000x reference)
; #define LAS __attribute__((address_space(3)))
; __global__ void __launch_bounds__(256, 2) fwd_megakernel(KArgs k) {
;   __shared__ __attribute__((aligned(16))) char smem_raw[SMEM_BYTES];
;   __shared__ uint4 xb_words;
;   cg::grid_group grid = cg::this_grid();
;   const Params p = make_params(k);
;   if (__builtin_amdgcn_workitem_id_x() == 0) xb_words = make_uint4(0u, 0u, 0u, 0u);
;   __syncthreads();
;   const XcdBarrier xb = xcd_barrier_post((unsigned*)(k.ws + O_bar), (volatile LAS unsigned*)&xb_words);
_Z14fwd_megakernel5KArgs:
	s_mov_b32 s8, s2
	s_load_dwordx16 s[48:63], s[0:1], 0x140
	s_load_dword s2, s[0:1], 0x188
	v_and_b32_e32 v210, 0x3ff, v0
	v_cmp_eq_u32_e64 s[4:5], 0, v210
	s_waitcnt lgkmcnt(0)
	v_writelane_b32 v252, s2, 0
	s_load_dwordx2 s[2:3], s[0:1], 0x180
	s_waitcnt lgkmcnt(0)
	v_writelane_b32 v252, s2, 1
	s_nop 1
	v_writelane_b32 v252, s3, 2
	s_lshr_b32 s3, s2, 1
	s_cmp_ge_u32 s8, s3
	s_cbranch_scc0 .Lprio_skip
	s_setprio 1
.Lprio_skip:
	s_add_u32 s2, s0, 0x180
	s_addc_u32 s3, s1, 0
	v_writelane_b32 v252, s2, 3
	s_nop 1
	v_writelane_b32 v252, s3, 4
	s_mov_b64 s[2:3], exec
	v_writelane_b32 v252, s4, 5
	s_nop 1
	v_writelane_b32 v252, s5, 6
	s_and_b64 s[4:5], s[2:3], s[4:5]
	s_mov_b64 exec, s[4:5]
	s_cbranch_execz .LBB0_2
	v_mov_b32_e32 v2, 0
	v_mov_b32_e32 v3, v2
	v_mov_b32_e32 v4, v2
	v_mov_b32_e32 v5, v2
	v_mov_b32_e32 v1, 0x12000
	ds_write_b128 v1, v[2:5]
